# P1 tail: ab_rows16 tasks taken by the 32 workgroups without a 128x128 tile (run beside the tiles instead of after them)
# speedup vs baseline: 1.0268x; 1.0268x over previous
; DEV void ab_rows16(const bf16_t* __restrict__ h, const bf16_t* __restrict__ wab, float* __restrict__ ab4, int rt, int kq, int lane) {
;     const int fr = lane & 15, fq = lane >> 4;
;     const bf16_t* ap = h + (size_t)(rt * 16 + fr) * LDB + kq * 512 + fq * 8;
;     const bf16_t* bp = wab + (size_t)fr * LDB + kq * 512 + fq * 8;
;     bf16x8 a[16], b[16];
; #pragma unroll
;     for (int s = 0; s < 16; ++s) { a[s] = *(const bf16x8*)(ap + s * 32); b[s] = *(const bf16x8*)(bp + s * 32); }
;     f32x4 acc = {0.f, 0.f, 0.f, 0.f};
; #pragma unroll
;     for (int s = 0; s < 16; ++s) acc = __builtin_amdgcn_mfma_f32_16x16x32_bf16(b[s], a[s], acc, 0, 0, 0);
;     *(f32x4*)(ab4 + (size_t)kq * TT * 16 + (size_t)(rt * 16 + fr) * 16 + fq * 4) = acc;
; __global__ void __launch_bounds__(512) hymba_fwd(Params p) {
;     ...
;         for (int tk = bid * 8 + wid; tk < (TT / 16) * 4; tk += G * 8) ab_rows16(hbuf, Wt_in + (size_t)NPJ * LDB, ab, tk >> 2, tk & 3, lane);
.LBB0_405:
	s_mov_b32 s96, s2
	s_mov_b32 s97, s33
	s_cmpk_lg_i32 s33, 0x100
	s_cbranch_scc1 .Labr_map_done
	s_mov_b32 s97, 32
	s_sub_i32 s96, s2, 0xe0
	s_cmp_ge_i32 s96, 0
	s_cbranch_scc1 .Labr_map_done
	s_movk_i32 s96, 0x1000
.Labr_map_done:
	v_ashrrev_i32_e32 v72, 6, v1
	v_lshl_add_u32 v70, s96, 3, v72
	s_movk_i32 s4, 0x880
	v_cmp_gt_i32_e32 vcc, s4, v70
	s_and_saveexec_b64 s[4:5], vcc
	s_cbranch_execz .LBB0_408
	v_and_b32_e32 v71, 15, v1
	v_mul_u32_u24_e32 v2, 0x840, v71
	v_lshlrev_b32_e32 v68, 1, v2
	v_mov_b32_e32 v69, 0
	v_lshl_add_u64 v[2:3], v[158:159], 0, v[68:69]
	v_and_b32_e32 v68, 48, v1
	v_bfe_u32 v1, v1, 6, 2
	v_lshl_add_u64 v[2:3], v[2:3], 0, v[68:69]
	v_lshlrev_b32_e32 v66, 10, v1
	v_mov_b32_e32 v67, v69
	v_lshl_add_u64 v[2:3], v[2:3], 0, v[66:67]
	s_mov_b64 s[6:7], 0x18c4000
	v_lshl_add_u64 v[62:63], v[2:3], 0, s[6:7]
	s_mov_b32 s6, 0x18c4000
	v_add_co_u32_e32 v64, vcc, s6, v2
	v_mul_u32_u24_e32 v1, 0x22000, v1
	s_nop 0
	v_addc_co_u32_e32 v65, vcc, 0, v3, vcc
	global_load_dwordx4 v[2:5], v[62:63], off offset:64
	global_load_dwordx4 v[6:9], v[62:63], off offset:128
	global_load_dwordx4 v[10:13], v[62:63], off offset:192
	global_load_dwordx4 v[14:17], v[62:63], off offset:256
	global_load_dwordx4 v[18:21], v[62:63], off offset:320
	global_load_dwordx4 v[22:25], v[62:63], off offset:384
	global_load_dwordx4 v[26:29], v[62:63], off offset:448
	global_load_dwordx4 v[30:33], v[62:63], off offset:512
	global_load_dwordx4 v[34:37], v[62:63], off offset:576
	global_load_dwordx4 v[38:41], v[62:63], off offset:640
	global_load_dwordx4 v[42:45], v[62:63], off offset:704
	global_load_dwordx4 v[46:49], v[62:63], off offset:768
	global_load_dwordx4 v[50:53], v[62:63], off offset:832
	global_load_dwordx4 v[54:57], v[62:63], off offset:896
	global_load_dwordx4 v[58:61], v[64:65], off
	s_nop 0
	global_load_dwordx4 v[62:65], v[62:63], off offset:960
	v_lshlrev_b32_e32 v74, 2, v1
	v_mov_b32_e32 v75, v69
	v_lshl_add_u64 v[66:67], v[166:167], 0, v[66:67]
	v_lshl_add_u64 v[74:75], v[158:159], 0, v[74:75]
	v_lshl_add_u64 v[66:67], v[66:67], 0, v[68:69]
	v_lshl_add_u64 v[68:69], v[74:75], 0, v[68:69]
	s_mov_b64 s[6:7], 0xd048000
	v_lshlrev_b32_e32 v1, 2, v72
	s_lshl_b32 s8, s97, 3
	v_lshl_add_u64 v[68:69], v[68:69], 0, s[6:7]
	v_lshl_add_u32 v1, s96, 5, v1
	s_lshl_b32 s9, s97, 5
	s_mov_b64 s[6:7], 0
	s_movk_i32 s10, 0x1080
	s_movk_i32 s11, 0x87f
